# S5 prompt item: U-tile loads all in flight, state GEMM LDS reads 2 k-steps ahead (3-stage ring), carry loop reads 1 iteration ahead; sample final-norm gains loaded once
# speedup vs baseline: 1.0066x; 1.0031x over previous
; #define LAS __attribute__((address_space(3)))
; #define S5_LAUNDER() int tid_ = tid0, lane_ = lane0; asm volatile("" : "+v"(tid_), "+v"(lane_)); const int tid = tid_, lane = lane_, fr = lane & 15, fq = lane >> 4; (void)tid; (void)fr; (void)fq
; __device__ __forceinline__ void s5_prompt_item_mfma(LAS unsigned char* lds, int tid0, int lane0, int wave, int n, int g, const bf16* USg, const bf16* FTg, const bf16* WTg, const bf16* GTg, ...
;     ...
;     { S5_LAUNDER(); const bf16* usrc = USg + ((size_t)g * M + (size_t)n * SEQ) * 16;
; #pragma unroll
;       for (int it = 0; it < 8; ++it) { const int q = tid + 512 * it, token = q >> 1, half = q & 1; const v4u v = *(const v4u*)(usrc + (size_t)token * 16 + 8 * half);
;           *(LAS v4u*)(lds + U_OFF + (token >> 5) * 1056 + (token & 31) * 32 + 16 * half) = v; } }
;     bf16x8 wa[16];
;     { S5_LAUNDER();
; #pragma unroll
;     for (int ks = 0; ks < 16; ++ks) wa[ks] = *(const bf16x8*)(WTg + ((size_t)(wave * 16 + ks) * 64 + lane) * 8);
;     }
;     __syncthreads();
.LBB0_848:
	s_and_b32 s65, s64, 31
	s_ashr_i32 s10, s64, 5
	s_lshl_b32 s8, s65, 15
	v_readlane_b32 s9, v254, 54
	s_add_u32 vcc_lo, s9, s8
	v_readlane_b32 s8, v254, 56
	s_addc_u32 vcc_hi, s8, 0
	s_lshl_b32 s8, s65, 17
	v_readlane_b32 s9, v253, 45
	s_add_u32 s72, s9, s8
	v_readlane_b32 s9, v253, 49
	s_addc_u32 s73, s9, 0
	v_readlane_b32 s9, v253, 51
	s_add_u32 s54, s9, s8
	v_readlane_b32 s8, v253, 55
	s_addc_u32 s55, s8, 0
	s_ashr_i32 s11, s10, 31
	s_mul_i32 s12, s65, 0x4200
	s_lshl_b64 s[8:9], s[10:11], 11
	s_add_u32 s12, s8, s12
	s_addc_u32 s13, s9, 0
	s_lshl_b64 s[12:13], s[12:13], 5
	s_mov_b32 s37, s74
	s_add_u32 s74, s74, s12
	s_mov_b32 s84, s75
	s_addc_u32 s75, s75, s13
	v_readlane_b32 s12, v252, 4
	v_readlane_b32 s13, v252, 5
	v_readlane_b32 s14, v252, 6
	v_readlane_b32 s15, v252, 7
	s_mov_b64 s[14:15], s[12:13]
	v_mov_b32_e32 v52, v192
	v_mov_b32_e32 v2, v196
	s_movk_i32 s11, 0x420
	v_ashrrev_i32_e32 v36, 1, v52
	v_ashrrev_i32_e32 v37, 31, v36
	s_waitcnt vmcnt(0)
	v_lshlrev_b64 v[4:5], 5, v[36:37]
	v_add_u32_e32 v37, 0x200, v52
	v_ashrrev_i32_e32 v38, 1, v37
	v_ashrrev_i32_e32 v39, 31, v38
	v_lshlrev_b64 v[6:7], 5, v[38:39]
	v_add_u32_e32 v39, 0x400, v52
	v_lshlrev_b32_e32 v2, 4, v52
	v_ashrrev_i32_e32 v40, 1, v39
	v_and_b32_e32 v2, 16, v2
	v_ashrrev_i32_e32 v41, 31, v40
	v_lshl_add_u64 v[32:33], s[74:75], 0, v[2:3]
	v_lshlrev_b64 v[12:13], 5, v[40:41]
	v_add_u32_e32 v41, 0x600, v52
	v_lshl_add_u64 v[4:5], v[32:33], 0, v[4:5]
	v_lshl_add_u64 v[8:9], v[32:33], 0, v[6:7]
	v_ashrrev_i32_e32 v42, 1, v41
	global_load_dwordx4 v[4:7], v[4:5], off
	s_nop 0
	global_load_dwordx4 v[8:11], v[8:9], off
	v_ashrrev_i32_e32 v43, 31, v42
	v_lshl_add_u64 v[12:13], v[32:33], 0, v[12:13]
	v_lshlrev_b64 v[16:17], 5, v[42:43]
	global_load_dwordx4 v[12:15], v[12:13], off
	v_lshl_add_u64 v[16:17], v[32:33], 0, v[16:17]
	v_add_u32_e32 v43, 0x800, v52
	global_load_dwordx4 v[16:19], v[16:17], off
	v_ashrrev_i32_e32 v44, 1, v43
	v_ashrrev_i32_e32 v45, 31, v44
	v_lshlrev_b64 v[20:21], 5, v[44:45]
	v_lshl_add_u64 v[20:21], v[32:33], 0, v[20:21]
	v_add_u32_e32 v45, 0xa00, v52
	global_load_dwordx4 v[20:23], v[20:21], off
	v_ashrrev_i32_e32 v46, 1, v45
	v_ashrrev_i32_e32 v47, 31, v46
	v_lshlrev_b64 v[24:25], 5, v[46:47]
	v_lshl_add_u64 v[24:25], v[32:33], 0, v[24:25]
	v_add_u32_e32 v47, 0xc00, v52
	global_load_dwordx4 v[24:27], v[24:25], off
	v_ashrrev_i32_e32 v48, 1, v47
	v_ashrrev_i32_e32 v49, 31, v48
	v_lshlrev_b64 v[28:29], 5, v[48:49]
	v_lshl_add_u64 v[28:29], v[32:33], 0, v[28:29]
	v_add_u32_e32 v49, 0xe00, v52
	global_load_dwordx4 v[28:31], v[28:29], off
	v_ashrrev_i32_e32 v50, 1, v49
	v_ashrrev_i32_e32 v51, 31, v50
	v_lshlrev_b64 v[34:35], 5, v[50:51]
	v_lshl_add_u64 v[32:33], v[32:33], 0, v[34:35]
	global_load_dwordx4 v[32:35], v[32:33], off
	v_ashrrev_i32_e32 v51, 6, v52
	v_mul_lo_u32 v51, v51, s11
	v_lshlrev_b32_e32 v36, 5, v36
	v_ashrrev_i32_e32 v37, 6, v37
	v_ashrrev_i32_e32 v39, 6, v39
	v_add_u32_e32 v51, 0, v51
	v_and_b32_e32 v36, 0x3e0, v36
	v_mul_lo_u32 v37, v37, s11
	v_lshlrev_b32_e32 v38, 5, v38
	v_mul_lo_u32 v39, v39, s11
	v_lshlrev_b32_e32 v40, 5, v40
	v_ashrrev_i32_e32 v41, 6, v41
	v_add3_u32 v36, v51, v36, v2
	v_add_u32_e32 v37, 0, v37
	v_and_b32_e32 v38, 0x3e0, v38
	v_add_u32_e32 v39, 0, v39
	v_and_b32_e32 v40, 0x3e0, v40
	v_add3_u32 v37, v37, v38, v2
	v_add3_u32 v38, v39, v40, v2
	s_waitcnt vmcnt(7)
	ds_write_b128 v36, v[4:7]
	s_waitcnt vmcnt(6)
	ds_write_b128 v37, v[8:11]
	s_waitcnt vmcnt(5)
	ds_write_b128 v38, v[12:15]
	v_mul_lo_u32 v4, v41, s11
	v_lshlrev_b32_e32 v5, 5, v42
	v_add_u32_e32 v4, 0, v4
	v_and_b32_e32 v5, 0x3e0, v5
	v_add3_u32 v4, v4, v5, v2
	s_waitcnt vmcnt(4)
	ds_write_b128 v4, v[16:19]
	v_ashrrev_i32_e32 v4, 6, v43
	v_mul_lo_u32 v4, v4, s11
	v_lshlrev_b32_e32 v5, 5, v44
	v_add_u32_e32 v4, 0, v4
	v_and_b32_e32 v5, 0x3e0, v5
	v_add3_u32 v4, v4, v5, v2
	s_waitcnt vmcnt(3)
	ds_write_b128 v4, v[20:23]
	v_ashrrev_i32_e32 v4, 6, v45
	v_mul_lo_u32 v4, v4, s11
	v_lshlrev_b32_e32 v5, 5, v46
	v_add_u32_e32 v4, 0, v4
	v_and_b32_e32 v5, 0x3e0, v5
	v_add3_u32 v4, v4, v5, v2
	s_waitcnt vmcnt(2)
	ds_write_b128 v4, v[24:27]
	v_ashrrev_i32_e32 v4, 6, v47
	v_mul_lo_u32 v4, v4, s11
	v_lshlrev_b32_e32 v5, 5, v48
	v_add_u32_e32 v4, 0, v4
	v_and_b32_e32 v5, 0x3e0, v5
	v_add3_u32 v4, v4, v5, v2
	s_waitcnt vmcnt(1)
	ds_write_b128 v4, v[28:31]
	v_ashrrev_i32_e32 v4, 6, v49
	v_mul_lo_u32 v4, v4, s11
	v_lshlrev_b32_e32 v5, 5, v50
	v_add_u32_e32 v4, 0, v4
	v_and_b32_e32 v5, 0x3e0, v5
	v_add3_u32 v2, v4, v5, v2
	s_waitcnt vmcnt(0)
	ds_write_b128 v2, v[32:35]
	v_mov_b32_e32 v2, v192
	v_mov_b32_e32 v4, v196
	v_mov_b32_e32 v48, v192
	v_ashrrev_i32_e32 v5, 31, v4
	v_lshl_add_u64 v[4:5], v[4:5], 4, s[72:73]
	v_readlane_b32 s72, v253, 41
	v_readlane_b32 s73, v253, 42
	v_mov_b32_e32 v2, v196
	s_movk_i32 s11, 0x4000
	v_lshl_add_u64 v[6:7], v[4:5], 0, s[72:73]
	global_load_dwordx4 v[50:53], v[6:7], off
	v_readlane_b32 s72, v253, 33
	v_readlane_b32 s73, v253, 34
	s_nop 1
	v_lshl_add_u64 v[6:7], v[4:5], 0, s[72:73]
	global_load_dwordx4 v[54:57], v[6:7], off
	v_readlane_b32 s72, v254, 23
	v_readlane_b32 s73, v254, 24
	s_nop 1
	v_lshl_add_u64 v[6:7], v[4:5], 0, s[72:73]
	v_readlane_b32 s72, v253, 43
	v_readlane_b32 s73, v253, 44
	s_nop 1
	v_lshl_add_u64 v[8:9], v[4:5], 0, s[72:73]
	global_load_dwordx4 v[58:61], v[6:7], off
	global_load_dwordx4 v[62:65], v[8:9], off
	v_readlane_b32 s72, v254, 46
	v_readlane_b32 s73, v254, 47
	s_nop 1
	v_lshl_add_u64 v[6:7], v[4:5], 0, s[72:73]
	v_readlane_b32 s72, v253, 31
	v_readlane_b32 s73, v253, 32
	s_nop 1
	v_lshl_add_u64 v[8:9], v[4:5], 0, s[72:73]
	v_readlane_b32 s72, v253, 35
	v_readlane_b32 s73, v253, 36
	global_load_dwordx4 v[66:69], v[6:7], off
	global_load_dwordx4 v[44:47], v[8:9], off
	v_lshl_add_u64 v[6:7], v[4:5], 0, s[72:73]
	v_readlane_b32 s72, v253, 37
	v_readlane_b32 s73, v253, 38
	s_nop 1
	v_lshl_add_u64 v[8:9], v[4:5], 0, s[72:73]
	v_readlane_b32 s72, v254, 19
	v_readlane_b32 s73, v254, 20
	global_load_dwordx4 v[40:43], v[6:7], off
	global_load_dwordx4 v[36:39], v[8:9], off
	v_lshl_add_u64 v[6:7], v[4:5], 0, s[72:73]
	v_readlane_b32 s72, v254, 48
	v_readlane_b32 s73, v254, 49
	s_nop 1
	v_lshl_add_u64 v[8:9], v[4:5], 0, s[72:73]
	v_readlane_b32 s72, v254, 50
	v_readlane_b32 s73, v254, 51
	global_load_dwordx4 v[32:35], v[6:7], off
	global_load_dwordx4 v[28:31], v[8:9], off
	v_lshl_add_u64 v[6:7], v[4:5], 0, s[72:73]
	v_readlane_b32 s72, v253, 39
	v_readlane_b32 s73, v253, 40
	s_nop 1
	v_lshl_add_u64 v[8:9], v[4:5], 0, s[72:73]
	v_readlane_b32 s72, v254, 52
	v_readlane_b32 s73, v254, 53
	global_load_dwordx4 v[24:27], v[6:7], off
	global_load_dwordx4 v[20:23], v[8:9], off
	v_lshl_add_u64 v[6:7], v[4:5], 0, s[72:73]
	v_lshl_add_u64 v[8:9], v[4:5], 0, s[80:81]
	global_load_dwordx4 v[16:19], v[6:7], off
	global_load_dwordx4 v[12:15], v[8:9], off
	v_lshl_add_u64 v[6:7], v[4:5], 0, s[76:77]
	v_lshl_add_u64 v[4:5], v[4:5], 0, s[30:31]
	global_load_dwordx4 v[8:11], v[6:7], off
	s_nop 0
	global_load_dwordx4 v[4:7], v[4:5], off
	s_waitcnt lgkmcnt(0)
	s_barrier
; #define LAS __attribute__((address_space(3)))
; #define S5_LAUNDER() int tid_ = tid0, lane_ = lane0; asm volatile("" : "+v"(tid_), "+v"(lane_)); const int tid = tid_, lane = lane_, fr = lane & 15, fq = lane >> 4; (void)tid; (void)fr; (void)fq
; __device__ __forceinline__ void s5_prompt_item_mfma(LAS unsigned char* lds, int tid0, int lane0, int wave, int n, int g, const bf16* USg, const bf16* FTg, const bf16* WTg, const bf16* GTg, ...
;     ...
;     {   S5_LAUNDER();
;         f32x4 accS[4];
; #pragma unroll
;         for (int cb = 0; cb < 4; ++cb) accS[cb] = (f32x4){0.f, 0.f, 0.f, 0.f};
; #pragma unroll
;         for (int ks = 0; ks < 16; ++ks) {
; #pragma unroll
;             for (int cb = 0; cb < 4; ++cb) { const bf16x8 b = *(const LAS bf16x8*)(lds + U_OFF + (16 * cb + fr) * 1056 + (2 * ks + (fq >> 1)) * 32 + 16 * (fq & 1));
;                 accS[cb] = __builtin_amdgcn_mfma_f32_16x16x32_bf16(wa[ks], b, accS[cb], 0, 0, 0); }
;             if (ks & 1) asm volatile("" ::: "memory"); }
; #pragma unroll
;         for (int cb = 0; cb < 4; ++cb) *(LAS f32x4*)(lds + R2_OFF + ((16 * cb + fr) * 132 + 16 * wave + 4 * fq) * 4) = accS[cb];
;     }
	s_nop 0
	v_and_b32_e32 v48, 15, v2
	v_and_b32_e32 v49, 0xffffffe0, v2
	v_add_u32_e32 v49, 0, v49
	v_and_b32_e32 v70, 16, v2
	v_mul_u32_u24_e32 v71, 0x420, v48
	v_add3_u32 v49, v49, v70, v71
	v_and_b32_e32 v2, -16, v2
	ds_read_b128 v[108:111], v49
	ds_read_b128 v[112:115], v49 offset:16896
	ds_read_b128 v[116:119], v49 offset:33792
	ds_read_b128 v[120:123], v49 offset:50688
	ds_read_b128 v[124:127], v49 offset:64
	ds_read_b128 v[128:131], v49 offset:16960
	ds_read_b128 v[132:135], v49 offset:33856
	ds_read_b128 v[136:139], v49 offset:50752
	ds_read_b128 v[140:143], v49 offset:128
	ds_read_b128 v[144:147], v49 offset:17024
	ds_read_b128 v[148:151], v49 offset:33920
	ds_read_b128 v[152:155], v49 offset:50816
	s_waitcnt vmcnt(15) lgkmcnt(8)
	v_mfma_f32_16x16x32_bf16 v[70:73], v[50:53], v[108:111], 0
	v_mfma_f32_16x16x32_bf16 v[74:77], v[50:53], v[112:115], 0
	v_mfma_f32_16x16x32_bf16 v[78:81], v[50:53], v[116:119], 0
	v_mfma_f32_16x16x32_bf16 v[82:85], v[50:53], v[120:123], 0
	ds_read_b128 v[108:111], v49 offset:192
	ds_read_b128 v[112:115], v49 offset:17088
	ds_read_b128 v[116:119], v49 offset:33984
	ds_read_b128 v[120:123], v49 offset:50880
	s_waitcnt vmcnt(14) lgkmcnt(8)
	v_mfma_f32_16x16x32_bf16 v[70:73], v[54:57], v[124:127], v[70:73]
	v_mfma_f32_16x16x32_bf16 v[74:77], v[54:57], v[128:131], v[74:77]
	v_mfma_f32_16x16x32_bf16 v[78:81], v[54:57], v[132:135], v[78:81]
	v_mfma_f32_16x16x32_bf16 v[82:85], v[54:57], v[136:139], v[82:85]
	ds_read_b128 v[124:127], v49 offset:256
	ds_read_b128 v[128:131], v49 offset:17152
	ds_read_b128 v[132:135], v49 offset:34048
	ds_read_b128 v[136:139], v49 offset:50944
	s_waitcnt vmcnt(13) lgkmcnt(8)
	v_mfma_f32_16x16x32_bf16 v[70:73], v[58:61], v[140:143], v[70:73]
	v_mfma_f32_16x16x32_bf16 v[74:77], v[58:61], v[144:147], v[74:77]
	v_mfma_f32_16x16x32_bf16 v[78:81], v[58:61], v[148:151], v[78:81]
	v_mfma_f32_16x16x32_bf16 v[82:85], v[58:61], v[152:155], v[82:85]
	ds_read_b128 v[140:143], v49 offset:320
	ds_read_b128 v[144:147], v49 offset:17216
	ds_read_b128 v[148:151], v49 offset:34112
	ds_read_b128 v[152:155], v49 offset:51008
	s_waitcnt vmcnt(12) lgkmcnt(8)
	v_mfma_f32_16x16x32_bf16 v[70:73], v[62:65], v[108:111], v[70:73]
	v_mfma_f32_16x16x32_bf16 v[74:77], v[62:65], v[112:115], v[74:77]
	v_mfma_f32_16x16x32_bf16 v[78:81], v[62:65], v[116:119], v[78:81]
	v_mfma_f32_16x16x32_bf16 v[82:85], v[62:65], v[120:123], v[82:85]
	ds_read_b128 v[108:111], v49 offset:384
	ds_read_b128 v[112:115], v49 offset:17280
	ds_read_b128 v[116:119], v49 offset:34176
	ds_read_b128 v[120:123], v49 offset:51072
	s_waitcnt vmcnt(11) lgkmcnt(8)
	v_mfma_f32_16x16x32_bf16 v[70:73], v[66:69], v[124:127], v[70:73]
	v_mfma_f32_16x16x32_bf16 v[74:77], v[66:69], v[128:131], v[74:77]
	v_mfma_f32_16x16x32_bf16 v[78:81], v[66:69], v[132:135], v[78:81]
	v_mfma_f32_16x16x32_bf16 v[82:85], v[66:69], v[136:139], v[82:85]
	ds_read_b128 v[124:127], v49 offset:448
	ds_read_b128 v[128:131], v49 offset:17344
	ds_read_b128 v[132:135], v49 offset:34240
	ds_read_b128 v[136:139], v49 offset:51136
	s_waitcnt vmcnt(10) lgkmcnt(8)
	v_mfma_f32_16x16x32_bf16 v[70:73], v[44:47], v[140:143], v[70:73]
	v_mfma_f32_16x16x32_bf16 v[74:77], v[44:47], v[144:147], v[74:77]
	v_mfma_f32_16x16x32_bf16 v[78:81], v[44:47], v[148:151], v[78:81]
	v_mfma_f32_16x16x32_bf16 v[82:85], v[44:47], v[152:155], v[82:85]
	ds_read_b128 v[140:143], v49 offset:512
	ds_read_b128 v[144:147], v49 offset:17408
	ds_read_b128 v[148:151], v49 offset:34304
	ds_read_b128 v[152:155], v49 offset:51200
	s_waitcnt vmcnt(9) lgkmcnt(8)
	v_mfma_f32_16x16x32_bf16 v[70:73], v[40:43], v[108:111], v[70:73]
	v_mfma_f32_16x16x32_bf16 v[74:77], v[40:43], v[112:115], v[74:77]
	v_mfma_f32_16x16x32_bf16 v[78:81], v[40:43], v[116:119], v[78:81]
	v_mfma_f32_16x16x32_bf16 v[82:85], v[40:43], v[120:123], v[82:85]
	ds_read_b128 v[108:111], v49 offset:576
	ds_read_b128 v[112:115], v49 offset:17472
	ds_read_b128 v[116:119], v49 offset:34368
	ds_read_b128 v[120:123], v49 offset:51264
	s_waitcnt vmcnt(8) lgkmcnt(8)
	v_mfma_f32_16x16x32_bf16 v[70:73], v[36:39], v[124:127], v[70:73]
	v_mfma_f32_16x16x32_bf16 v[74:77], v[36:39], v[128:131], v[74:77]
	v_mfma_f32_16x16x32_bf16 v[78:81], v[36:39], v[132:135], v[78:81]
	v_mfma_f32_16x16x32_bf16 v[82:85], v[36:39], v[136:139], v[82:85]
	ds_read_b128 v[124:127], v49 offset:640
	ds_read_b128 v[128:131], v49 offset:17536
	ds_read_b128 v[132:135], v49 offset:34432
	ds_read_b128 v[136:139], v49 offset:51328
	s_waitcnt vmcnt(7) lgkmcnt(8)
	v_mfma_f32_16x16x32_bf16 v[70:73], v[32:35], v[140:143], v[70:73]
	v_mfma_f32_16x16x32_bf16 v[74:77], v[32:35], v[144:147], v[74:77]
	v_mfma_f32_16x16x32_bf16 v[78:81], v[32:35], v[148:151], v[78:81]
	v_mfma_f32_16x16x32_bf16 v[82:85], v[32:35], v[152:155], v[82:85]
	ds_read_b128 v[140:143], v49 offset:704
	ds_read_b128 v[144:147], v49 offset:17600
	ds_read_b128 v[148:151], v49 offset:34496
	ds_read_b128 v[152:155], v49 offset:51392
	s_waitcnt vmcnt(6) lgkmcnt(8)
	v_mfma_f32_16x16x32_bf16 v[70:73], v[28:31], v[108:111], v[70:73]
	v_mfma_f32_16x16x32_bf16 v[74:77], v[28:31], v[112:115], v[74:77]
	v_mfma_f32_16x16x32_bf16 v[78:81], v[28:31], v[116:119], v[78:81]
	v_mfma_f32_16x16x32_bf16 v[82:85], v[28:31], v[120:123], v[82:85]
	ds_read_b128 v[108:111], v49 offset:768
	ds_read_b128 v[112:115], v49 offset:17664
	ds_read_b128 v[116:119], v49 offset:34560
	ds_read_b128 v[120:123], v49 offset:51456
	s_waitcnt vmcnt(5) lgkmcnt(8)
; #define LAS __attribute__((address_space(3)))
; __device__ __forceinline__ unsigned pk2(float lo, float hi) { unsigned r; asm("v_cvt_pk_bf16_f32 %0, %1, %2" : "=v"(r) : "v"(lo), "v"(hi)); return r; }
; #define S5_LAUNDER() int tid_ = tid0, lane_ = lane0; asm volatile("" : "+v"(tid_), "+v"(lane_)); const int tid = tid_, lane = lane_, fr = lane & 15, fq = lane >> 4; (void)tid; (void)fr; (void)fq
; __device__ __forceinline__ void s5_prompt_item_mfma(LAS unsigned char* lds, int tid0, int lane0, int wave, int n, int g, const bf16* USg, const bf16* FTg, const bf16* WTg, const bf16* GTg, ...
;     ...
;         for (int ks = 0; ks < 16; ++ks) {
; #pragma unroll
;             for (int cb = 0; cb < 4; ++cb) { const bf16x8 b = *(const LAS bf16x8*)(lds + U_OFF + (16 * cb + fr) * 1056 + (2 * ks + (fq >> 1)) * 32 + 16 * (fq & 1));
;                 accS[cb] = __builtin_amdgcn_mfma_f32_16x16x32_bf16(wa[ks], b, accS[cb], 0, 0, 0); }
;             if (ks & 1) asm volatile("" ::: "memory"); }
; #pragma unroll
;         for (int cb = 0; cb < 4; ++cb) *(LAS f32x4*)(lds + R2_OFF + ((16 * cb + fr) * 132 + 16 * wave + 4 * fq) * 4) = accS[cb];
;     }
;     __syncthreads();
;     const int tau0 = wave, tau1 = 15 - wave, tau2 = 16 + wave, tau3 = 31 - wave;
;     bf16x8 ga[4][4]; v4u ftq[4];
;     { S5_LAUNDER();
; #pragma unroll
;       for (int it = 0; it < 4; ++it) { const int q = tid + 512 * it; ftq[it] = *(const v4u*)(FTg + (size_t)q * 8); }
; #pragma unroll
;       for (int kk = 0; kk < 4; ++kk) { ga[0][kk] = *(const bf16x8*)(GTg + ((size_t)(tau0 * 4 + kk) * 64 + lane) * 8); ga[1][kk] = *(const bf16x8*)(GTg + ((size_t)(tau1 * 4 + kk) * 64 + lane) * 8);
;                                        ga[2][kk] = *(const bf16x8*)(GTg + ((size_t)(tau2 * 4 + kk) * 64 + lane) * 8); ga[3][kk] = *(const bf16x8*)(GTg + ((size_t)(tau3 * 4 + kk) * 64 + lane) * 8); } }
;     { S5_LAUNDER(); if (tid < 64) {
;         const int p = tid; const float lr = ltp[2 * p], li = ltp[2 * p + 1]; float hr = 0.f, hi = 0.f;
; #pragma unroll 8
;         for (int c = 0; c < S5NC; ++c) { *(LAS unsigned*)(lds + HP_OFF + c * 272 + 4 * p) = pk2(hr, hi);
;             const f32x2 sv = *(const LAS f32x2*)(lds + R2_OFF + (c * 132 + 2 * p) * 4);
;             const float nr = lr * hr - li * hi + sv.x, ni = lr * hi + li * hr + sv.y; hr = nr; hi = ni; }
	v_mfma_f32_16x16x32_bf16 v[70:73], v[24:27], v[124:127], v[70:73]
	v_mfma_f32_16x16x32_bf16 v[74:77], v[24:27], v[128:131], v[74:77]
	v_mfma_f32_16x16x32_bf16 v[78:81], v[24:27], v[132:135], v[78:81]
	v_mfma_f32_16x16x32_bf16 v[82:85], v[24:27], v[136:139], v[82:85]
	ds_read_b128 v[124:127], v49 offset:832
	ds_read_b128 v[128:131], v49 offset:17728
	ds_read_b128 v[132:135], v49 offset:34624
	ds_read_b128 v[136:139], v49 offset:51520
	s_waitcnt vmcnt(4) lgkmcnt(8)
	v_mfma_f32_16x16x32_bf16 v[70:73], v[20:23], v[140:143], v[70:73]
	v_mfma_f32_16x16x32_bf16 v[74:77], v[20:23], v[144:147], v[74:77]
	v_mfma_f32_16x16x32_bf16 v[78:81], v[20:23], v[148:151], v[78:81]
	v_mfma_f32_16x16x32_bf16 v[82:85], v[20:23], v[152:155], v[82:85]
	ds_read_b128 v[140:143], v49 offset:896
	ds_read_b128 v[144:147], v49 offset:17792
	ds_read_b128 v[148:151], v49 offset:34688
	ds_read_b128 v[152:155], v49 offset:51584
	s_waitcnt vmcnt(3) lgkmcnt(8)
	v_mfma_f32_16x16x32_bf16 v[70:73], v[16:19], v[108:111], v[70:73]
	v_mfma_f32_16x16x32_bf16 v[74:77], v[16:19], v[112:115], v[74:77]
	v_mfma_f32_16x16x32_bf16 v[78:81], v[16:19], v[116:119], v[78:81]
	v_mfma_f32_16x16x32_bf16 v[82:85], v[16:19], v[120:123], v[82:85]
	ds_read_b128 v[108:111], v49 offset:960
	ds_read_b128 v[112:115], v49 offset:17856
	ds_read_b128 v[116:119], v49 offset:34752
	ds_read_b128 v[120:123], v49 offset:51648
	s_waitcnt vmcnt(2) lgkmcnt(8)
	v_mfma_f32_16x16x32_bf16 v[70:73], v[12:15], v[124:127], v[70:73]
	v_mfma_f32_16x16x32_bf16 v[74:77], v[12:15], v[128:131], v[74:77]
	v_mfma_f32_16x16x32_bf16 v[78:81], v[12:15], v[132:135], v[78:81]
	v_mfma_f32_16x16x32_bf16 v[82:85], v[12:15], v[136:139], v[82:85]
	s_waitcnt vmcnt(1) lgkmcnt(4)
	v_mfma_f32_16x16x32_bf16 v[70:73], v[8:11], v[140:143], v[70:73]
	v_mfma_f32_16x16x32_bf16 v[74:77], v[8:11], v[144:147], v[74:77]
	v_mfma_f32_16x16x32_bf16 v[78:81], v[8:11], v[148:151], v[78:81]
	v_mfma_f32_16x16x32_bf16 v[82:85], v[8:11], v[152:155], v[82:85]
	s_waitcnt vmcnt(0) lgkmcnt(0)
	v_mfma_f32_16x16x32_bf16 v[70:73], v[4:7], v[108:111], v[70:73]
	v_mfma_f32_16x16x32_bf16 v[74:77], v[4:7], v[112:115], v[74:77]
	v_mfma_f32_16x16x32_bf16 v[78:81], v[4:7], v[116:119], v[78:81]
	v_mfma_f32_16x16x32_bf16 v[82:85], v[4:7], v[120:123], v[82:85]
	s_nop 7
	v_mul_u32_u24_e32 v8, 0x210, v48
	v_add3_u32 v2, s36, v2, v8
	ds_write_b128 v2, v[70:73]
	ds_write_b128 v2, v[74:77] offset:8448
	ds_write_b128 v2, v[78:81] offset:16896
	ds_write_b128 v2, v[82:85] offset:25344
	v_mov_b32_e32 v4, v192
	v_mov_b32_e32 v6, v196
	s_waitcnt lgkmcnt(0)
	s_barrier
	v_mov_b32_e32 v2, v196
	v_ashrrev_i32_e32 v5, 31, v4
	v_lshl_add_u64 v[4:5], v[4:5], 4, vcc
	v_add_co_u32_e32 v8, vcc, s33, v4
	v_ashrrev_i32_e32 v7, 31, v6
	s_nop 0
	v_addc_co_u32_e32 v9, vcc, 0, v5, vcc
	v_add_co_u32_e32 v10, vcc, s11, v4
	s_movk_i32 s11, 0x6000
	s_nop 0
	v_addc_co_u32_e32 v11, vcc, 0, v5, vcc
	v_add_co_u32_e32 v12, vcc, s11, v4
	v_lshl_add_u64 v[6:7], v[6:7], 4, s[54:55]
	s_nop 0
	v_addc_co_u32_e32 v13, vcc, 0, v5, vcc
	global_load_dwordx4 v[24:27], v[4:5], off
	global_load_dwordx4 v[28:31], v[8:9], off
	global_load_dwordx4 v[32:35], v[10:11], off
	global_load_dwordx4 v[36:39], v[12:13], off
	v_lshl_add_u64 v[4:5], v[6:7], 0, s[34:35]
	v_lshl_add_u64 v[8:9], v[6:7], 0, s[38:39]
	global_load_dwordx4 v[152:155], v[4:5], off
	global_load_dwordx4 v[124:127], v[8:9], off
	v_lshl_add_u64 v[4:5], v[6:7], 0, s[2:3]
	v_lshl_add_u64 v[8:9], v[6:7], 0, s[0:1]
	global_load_dwordx4 v[108:111], v[4:5], off
	global_load_dwordx4 v[16:19], v[8:9], off
	v_lshl_add_u64 v[4:5], v[6:7], 0, s[4:5]
	v_lshl_add_u64 v[8:9], v[6:7], 0, s[28:29]
	global_load_dwordx4 v[140:143], v[4:5], off
	global_load_dwordx4 v[128:131], v[8:9], off
	v_lshl_add_u64 v[4:5], v[6:7], 0, s[18:19]
	v_lshl_add_u64 v[8:9], v[6:7], 0, s[92:93]
	global_load_dwordx4 v[112:115], v[4:5], off
	global_load_dwordx4 v[12:15], v[8:9], off
	v_lshl_add_u64 v[4:5], v[6:7], 0, s[96:97]
	v_lshl_add_u64 v[8:9], v[6:7], 0, s[40:41]
	global_load_dwordx4 v[144:147], v[4:5], off
	global_load_dwordx4 v[132:135], v[8:9], off
	v_lshl_add_u64 v[4:5], v[6:7], 0, s[42:43]
	v_lshl_add_u64 v[8:9], v[6:7], 0, s[44:45]
	global_load_dwordx4 v[116:119], v[4:5], off
	s_nop 0
	global_load_dwordx4 v[8:11], v[8:9], off
	v_lshl_add_u64 v[4:5], v[6:7], 0, s[46:47]
	v_lshl_add_u64 v[20:21], v[6:7], 0, s[48:49]
	global_load_dwordx4 v[148:151], v[4:5], off
	global_load_dwordx4 v[136:139], v[20:21], off
	v_lshl_add_u64 v[4:5], v[6:7], 0, s[50:51]
	v_lshl_add_u64 v[6:7], v[6:7], 0, s[88:89]
	global_load_dwordx4 v[120:123], v[4:5], off
	s_nop 0
	global_load_dwordx4 v[4:7], v[6:7], off
	v_mov_b32_e32 v20, v192
	s_nop 0
	v_cmp_gt_i32_e32 vcc, 64, v20
	s_and_saveexec_b64 s[54:55], vcc
	s_cbranch_execz .LBB0_852
	v_readlane_b32 s72, v254, 32
	s_or_b32 s11, s72, s65
	s_mulk_i32 s11, 0x4200
	v_readlane_b32 s72, v253, 63
	v_readlane_b32 s73, v254, 33
	s_add_u32 s72, s72, s11
	v_readlane_b32 s11, v254, 1
	v_lshlrev_b32_e32 v22, 1, v20
	s_addc_u32 s73, s11, 0
	v_ashrrev_i32_e32 v23, 31, v22
	v_lshl_add_u64 v[22:23], v[22:23], 2, s[72:73]
	global_load_dwordx2 v[22:23], v[22:23], off
	v_mov_b32_e32 v42, 0
	v_lshlrev_b32_e32 v2, 2, v20
	v_lshlrev_b32_e32 v21, 3, v20
	s_mov_b32 s11, 64
	v_mov_b32_e32 v43, v42
	s_waitcnt vmcnt(0)
	v_pk_mov_b32 v[40:41], v[22:23], v[22:23] op_sel:[1,0]
	v_add_u32_e32 v84, 0x10800, v21
	ds_read_b64 v[68:69], v84
	ds_read_b64 v[70:71], v84 offset:528
	ds_read_b64 v[72:73], v84 offset:1056
	ds_read_b64 v[74:75], v84 offset:1584
	ds_read_b64 v[76:77], v84 offset:2112
	ds_read_b64 v[78:79], v84 offset:2640
	ds_read_b64 v[80:81], v84 offset:3168
	ds_read_b64 v[82:83], v84 offset:3696
; #define LAS __attribute__((address_space(3)))
; __device__ __forceinline__ unsigned pk2(float lo, float hi) { unsigned r; asm("v_cvt_pk_bf16_f32 %0, %1, %2" : "=v"(r) : "v"(lo), "v"(hi)); return r; }
; #define S5_LAUNDER() int tid_ = tid0, lane_ = lane0; asm volatile("" : "+v"(tid_), "+v"(lane_)); const int tid = tid_, lane = lane_, fr = lane & 15, fq = lane >> 4; (void)tid; (void)fr; (void)fq
; __device__ __forceinline__ void s5_prompt_item_mfma(LAS unsigned char* lds, int tid0, int lane0, int wave, int n, int g, const bf16* USg, const bf16* FTg, const bf16* WTg, const bf16* GTg, ...
;     ...
;     { S5_LAUNDER(); if (tid < 64) {
;         const int p = tid; const float lr = ltp[2 * p], li = ltp[2 * p + 1]; float hr = 0.f, hi = 0.f;
; #pragma unroll 8
;         for (int c = 0; c < S5NC; ++c) { *(LAS unsigned*)(lds + HP_OFF + c * 272 + 4 * p) = pk2(hr, hi);
;             const f32x2 sv = *(const LAS f32x2*)(lds + R2_OFF + (c * 132 + 2 * p) * 4);
;             const float nr = lr * hr - li * hi + sv.x, ni = lr * hi + li * hr + sv.y; hr = nr; hi = ni; }
;         out_re[p] = hr; out_im[p] = hi;
;     } }
.LBB0_850:
	s_waitcnt lgkmcnt(0)
	v_mov_b64_e32 v[52:53], v[68:69]
	v_mov_b64_e32 v[54:55], v[70:71]
	v_mov_b64_e32 v[56:57], v[72:73]
	v_mov_b64_e32 v[58:59], v[74:75]
	v_mov_b64_e32 v[60:61], v[76:77]
	v_mov_b64_e32 v[62:63], v[78:79]
	v_mov_b64_e32 v[64:65], v[80:81]
	v_mov_b64_e32 v[66:67], v[82:83]
	v_add_u32_e32 v84, 0x11880, v21
	ds_read_b64 v[68:69], v84
	ds_read_b64 v[70:71], v84 offset:528
	ds_read_b64 v[72:73], v84 offset:1056
	ds_read_b64 v[74:75], v84 offset:1584
	ds_read_b64 v[76:77], v84 offset:2112
	ds_read_b64 v[78:79], v84 offset:2640
	ds_read_b64 v[80:81], v84 offset:3168
	ds_read_b64 v[82:83], v84 offset:3696
	v_add_u32_e32 v50, 0, v2
	v_cvt_pk_bf16_f32 v44, v42, v43
	v_add_u32_e32 v45, 0x18c00, v50
	v_add_u32_e32 v51, 0, v21
	ds_write_b32 v45, v44
	v_pk_mul_f32 v[46:47], v[40:41], v[42:43] op_sel:[0,1]
	s_add_i32 s11, s11, -8
	v_pk_fma_f32 v[48:49], v[22:23], v[42:43], v[46:47] neg_lo:[0,0,1] neg_hi:[0,0,1]
	v_pk_fma_f32 v[42:43], v[22:23], v[42:43], v[46:47] op_sel_hi:[1,0,1]
	v_add_u32_e32 v21, 0x1080, v21
	v_mov_b32_e32 v49, v43
	v_pk_add_f32 v[42:43], v[48:49], v[52:53]
	v_add_u32_e32 v45, 0x18d10, v50
	v_cvt_pk_bf16_f32 v44, v42, v43
	ds_write_b32 v45, v44
	v_pk_mul_f32 v[46:47], v[40:41], v[42:43] op_sel:[0,1]
	s_cmp_eq_u32 s11, 0
	v_pk_fma_f32 v[48:49], v[22:23], v[42:43], v[46:47] neg_lo:[0,0,1] neg_hi:[0,0,1]
	v_pk_fma_f32 v[42:43], v[22:23], v[42:43], v[46:47] op_sel_hi:[1,0,1]
	v_add_u32_e32 v2, 0x880, v2
	v_mov_b32_e32 v49, v43
	v_pk_add_f32 v[42:43], v[48:49], v[54:55]
	v_add_u32_e32 v45, 0x18e20, v50
	v_cvt_pk_bf16_f32 v44, v42, v43
	ds_write_b32 v45, v44
	v_pk_mul_f32 v[46:47], v[40:41], v[42:43] op_sel:[0,1]
	s_nop 0
	v_pk_fma_f32 v[48:49], v[22:23], v[42:43], v[46:47] neg_lo:[0,0,1] neg_hi:[0,0,1]
	v_pk_fma_f32 v[42:43], v[22:23], v[42:43], v[46:47] op_sel_hi:[1,0,1]
	s_nop 0
	v_mov_b32_e32 v49, v43
	v_pk_add_f32 v[42:43], v[48:49], v[56:57]
	v_add_u32_e32 v45, 0x18f30, v50
	v_cvt_pk_bf16_f32 v44, v42, v43
	ds_write_b32 v45, v44
	v_pk_mul_f32 v[46:47], v[40:41], v[42:43] op_sel:[0,1]
	s_nop 0
	v_pk_fma_f32 v[48:49], v[22:23], v[42:43], v[46:47] neg_lo:[0,0,1] neg_hi:[0,0,1]
	v_pk_fma_f32 v[42:43], v[22:23], v[42:43], v[46:47] op_sel_hi:[1,0,1]
	s_nop 0
	v_mov_b32_e32 v49, v43
	v_pk_add_f32 v[42:43], v[48:49], v[58:59]
	v_add_u32_e32 v45, 0x19040, v50
	v_cvt_pk_bf16_f32 v44, v42, v43
	ds_write_b32 v45, v44
	v_pk_mul_f32 v[46:47], v[40:41], v[42:43] op_sel:[0,1]
	s_nop 0
	v_pk_fma_f32 v[48:49], v[22:23], v[42:43], v[46:47] neg_lo:[0,0,1] neg_hi:[0,0,1]
	v_pk_fma_f32 v[42:43], v[22:23], v[42:43], v[46:47] op_sel_hi:[1,0,1]
	s_nop 0
	v_mov_b32_e32 v49, v43
	v_pk_add_f32 v[42:43], v[48:49], v[60:61]
	v_add_u32_e32 v45, 0x19150, v50
	v_cvt_pk_bf16_f32 v44, v42, v43
	ds_write_b32 v45, v44
	v_pk_mul_f32 v[46:47], v[40:41], v[42:43] op_sel:[0,1]
	s_nop 0
	v_pk_fma_f32 v[48:49], v[22:23], v[42:43], v[46:47] neg_lo:[0,0,1] neg_hi:[0,0,1]
	v_pk_fma_f32 v[42:43], v[22:23], v[42:43], v[46:47] op_sel_hi:[1,0,1]
	s_nop 0
	v_mov_b32_e32 v49, v43
	v_pk_add_f32 v[42:43], v[48:49], v[62:63]
	v_add_u32_e32 v45, 0x19260, v50
	v_cvt_pk_bf16_f32 v44, v42, v43
	ds_write_b32 v45, v44
	v_pk_mul_f32 v[46:47], v[40:41], v[42:43] op_sel:[0,1]
	s_nop 0
	v_pk_fma_f32 v[48:49], v[22:23], v[42:43], v[46:47] neg_lo:[0,0,1] neg_hi:[0,0,1]
	v_pk_fma_f32 v[42:43], v[22:23], v[42:43], v[46:47] op_sel_hi:[1,0,1]
	s_nop 0
	v_mov_b32_e32 v49, v43
	v_pk_add_f32 v[42:43], v[48:49], v[64:65]
	v_add_u32_e32 v45, 0x19370, v50
	v_cvt_pk_bf16_f32 v44, v42, v43
	ds_write_b32 v45, v44
	v_pk_mul_f32 v[46:47], v[40:41], v[42:43] op_sel:[0,1]
	s_nop 0
	v_pk_fma_f32 v[48:49], v[22:23], v[42:43], v[46:47] neg_lo:[0,0,1] neg_hi:[0,0,1]
	v_pk_fma_f32 v[42:43], v[22:23], v[42:43], v[46:47] op_sel_hi:[1,0,1]
	s_nop 0
	v_mov_b32_e32 v49, v43
	v_pk_add_f32 v[42:43], v[48:49], v[66:67]
	s_cbranch_scc0 .LBB0_850
	s_waitcnt lgkmcnt(0)
	v_readlane_b32 s11, v253, 29
	s_add_i32 s10, s10, s11
	s_ashr_i32 s11, s10, 31
	s_lshl_b64 s[10:11], s[10:11], 13
	s_lshl_b32 s72, s65, 8
	s_or_b32 s10, s10, s72
	s_add_u32 s14, s14, s10
	v_ashrrev_i32_e32 v21, 31, v20
	s_addc_u32 s15, s15, s11
	v_lshlrev_b64 v[20:21], 2, v[20:21]
	s_add_u32 s10, s12, s10
	v_lshl_add_u64 v[22:23], s[14:15], 0, v[20:21]
	s_addc_u32 s11, s13, s11
	v_add_co_u32_e32 v22, vcc, 0x4200000, v22
	v_lshl_add_u64 v[20:21], s[10:11], 0, v[20:21]
	s_nop 0
	v_addc_co_u32_e32 v23, vcc, 0, v23, vcc
	v_add_co_u32_e32 v20, vcc, 0x4220000, v20
	global_store_dword v[22:23], v42, off
	s_nop 0
	v_addc_co_u32_e32 v21, vcc, 0, v21, vcc
	global_store_dword v[20:21], v43, off

; #define GAS __attribute__((address_space(1)))
; __device__ __forceinline__ float bflo(unsigned w) { return __uint_as_float(w << 16); }
; __device__ __forceinline__ float bfhi(unsigned w) { return __uint_as_float(w & 0xffff0000u); }
; __device__ __forceinline__ void final_norm_rows(float* y, const bf16* hz, const float* ssq, const float* gf, int m_lo, int m_hi, int widx, int nw, int lane) {
;     for (int m0 = m_lo + widx; m0 < m_hi; m0 += 3 * nw) {
;         f32x4 sp[3][4]; v4u hq[3][2];
; #pragma unroll
;         for (int q = 0; q < 3; ++q) { const int m = m0 + q * nw; if (m < m_hi) { const f32x4* p = (const f32x4*)(ssq + (size_t)m * 16); sp[q][0] = p[0]; sp[q][1] = p[1]; sp[q][2] = p[2]; sp[q][3] = p[3];
;             const GAS v4u* hr = (const GAS v4u*)(hz + (size_t)m * DM) + lane; hq[q][0] = hr[0]; hq[q][1] = hr[64]; } }
; #pragma unroll
;         for (int q = 0; q < 3; ++q) { const int m = m0 + q * nw; if (m < m_hi) { float s = 0.f;
; #pragma unroll
;             for (int j = 0; j < 4; ++j) s += (sp[q][j][0] + sp[q][j][1]) + (sp[q][j][2] + sp[q][j][3]);
;             const float r = __builtin_amdgcn_rsqf(s * (1.0f / 1024.0f) + NORM_EPS);
;             GAS f32x4* yr = (GAS f32x4*)(y + (size_t)m * DM); const GAS f32x4* gr = (const GAS f32x4*)gf;
; #pragma unroll
;             for (int j = 0; j < 2; ++j) { const v4u w = hq[q][j]; const int c = 2 * (lane + 64 * j);
;                 const f32x4 g0 = gr[c], g1 = gr[c + 1];
;                 yr[c] = (f32x4){bflo(w.x) * r * g0[0], bfhi(w.x) * r * g0[1], bflo(w.y) * r * g0[2], bfhi(w.y) * r * g0[3]};
;                 yr[c + 1] = (f32x4){bflo(w.z) * r * g1[0], bfhi(w.z) * r * g1[1], bflo(w.w) * r * g1[2], bfhi(w.w) * r * g1[3]}; } } }
; __global__ void __launch_bounds__(NWAVES * 64, 2) hymba_fwd(Args args) {
;     ...
;                             if (tid == 0) {
;                                 const unsigned old = xb_add(ctlw + CW_FINS + rb * 64, 1u);
;                                 if (old == 15u) { __builtin_amdgcn_fence(__ATOMIC_ACQUIRE, "agent"); asm volatile("s_waitcnt vmcnt(0)" ::: "memory"); }
;                                 MISC[16] = (old == 15u) ? 1u : 0u; }
;                             __syncthreads();
;                             if (MISC[16] != 0u) final_norm_rows(out_ + O_Y, HOUT7, SB, GIN(I_GFIN), MP + 32 * rb, MP + 32 * rb + 32, wave, NWAVES, lane);
.LBB0_1966:
	s_or_b64 exec, exec, s[18:19]
	v_readlane_b32 s8, v253, 22
	s_waitcnt lgkmcnt(0)
	s_barrier
	v_mov_b32_e32 v4, s8
	ds_read_b32 v4, v4
	s_waitcnt lgkmcnt(0)
	v_cmp_eq_u32_e32 vcc, 0, v4
	s_cbranch_vccnz .LBB0_1959
	v_readlane_b32 s36, v252, 63
	s_lshl_b32 s8, s7, 5
	v_readlane_b32 s50, v253, 13
	v_readlane_b32 s51, v253, 14
	s_add_i32 s7, s8, 0x4020
	s_add_i32 s18, s4, s8
	s_mov_b64 s[20:21], s[50:51]
	s_cmp_ge_i32 s18, s7
	v_readlane_b32 s37, v253, 0
	v_readlane_b32 s38, v253, 1
	v_readlane_b32 s39, v253, 2
	v_readlane_b32 s40, v253, 3
	v_readlane_b32 s41, v253, 4
	v_readlane_b32 s42, v253, 5
	v_readlane_b32 s43, v253, 6
	v_readlane_b32 s44, v253, 7
	v_readlane_b32 s45, v253, 8
	v_readlane_b32 s46, v253, 9
	v_readlane_b32 s47, v253, 10
	v_readlane_b32 s48, v253, 11
	v_readlane_b32 s49, v253, 12
	s_cbranch_scc1 .LBB0_1959
	s_add_i32 s8, s5, s8
	s_ashr_i32 s19, s18, 31
	s_ashr_i32 s9, s8, 31
	v_lshl_add_u64 v[84:85], s[20:21], 0, v[2:3]
	global_load_dwordx4 v[120:123], v[84:85], off
	global_load_dwordx4 v[124:127], v[84:85], off offset:16
	global_load_dwordx4 v[128:131], v[84:85], off offset:2048
	global_load_dwordx4 v[132:135], v[84:85], off offset:2064
	s_lshl_b64 s[20:21], s[18:19], 6
	s_lshl_b64 s[22:23], s[8:9], 12
	s_add_u32 s22, s26, s22
	s_addc_u32 s23, s27, s23
	s_lshl_b64 s[24:25], s[18:19], 11
	v_lshl_add_u64 v[86:87], v[82:83], 0, s[24:25]
	s_lshl_b64 s[24:25], s[8:9], 11
	v_lshl_add_u64 v[88:89], v[82:83], 0, s[24:25]
	s_lshl_b64 s[24:25], s[18:19], 12
	s_add_u32 s24, s26, s24
	s_addc_u32 s25, s27, s25
	s_lshl_b64 s[40:41], s[8:9], 6
	s_mov_b64 s[42:43], s[10:11]
	s_branch .LBB0_1970

; #define GAS __attribute__((address_space(1)))
; __device__ __forceinline__ float bflo(unsigned w) { return __uint_as_float(w << 16); }
; __device__ __forceinline__ float bfhi(unsigned w) { return __uint_as_float(w & 0xffff0000u); }
; __device__ __forceinline__ void final_norm_rows(float* y, const bf16* hz, const float* ssq, const float* gf, int m_lo, int m_hi, int widx, int nw, int lane) {
;     ...
;         for (int q = 0; q < 3; ++q) { const int m = m0 + q * nw; if (m < m_hi) { float s = 0.f;
; #pragma unroll
;             for (int j = 0; j < 4; ++j) s += (sp[q][j][0] + sp[q][j][1]) + (sp[q][j][2] + sp[q][j][3]);
;             const float r = __builtin_amdgcn_rsqf(s * (1.0f / 1024.0f) + NORM_EPS);
;             GAS f32x4* yr = (GAS f32x4*)(y + (size_t)m * DM); const GAS f32x4* gr = (const GAS f32x4*)gf;
; #pragma unroll
;             for (int j = 0; j < 2; ++j) { const v4u w = hq[q][j]; const int c = 2 * (lane + 64 * j);
;                 const f32x4 g0 = gr[c], g1 = gr[c + 1];
;                 yr[c] = (f32x4){bflo(w.x) * r * g0[0], bfhi(w.x) * r * g0[1], bflo(w.y) * r * g0[2], bfhi(w.y) * r * g0[3]};
;                 yr[c + 1] = (f32x4){bflo(w.z) * r * g1[0], bfhi(w.z) * r * g1[1], bflo(w.w) * r * g1[2], bfhi(w.w) * r * g1[3]}; } } }
.LBB0_1974:
	s_waitcnt vmcnt(2)
	v_mov_b32_e32 v90, v73
	v_mov_b32_e32 v91, v74
	v_mov_b32_e32 v73, v75
	v_mov_b32_e32 v74, v69
	v_mov_b32_e32 v75, v70
	v_mov_b32_e32 v69, v71
	v_pk_add_f32 v[72:73], v[90:91], v[72:73]
	v_pk_add_f32 v[68:69], v[74:75], v[68:69]
	v_add_f32_e32 v72, v72, v73
	v_pk_add_f32 v[68:69], v[68:69], v[68:69] op_sel:[0,1] op_sel_hi:[1,0]
	v_add_f32_e32 v72, 0, v72
	v_add_f32_e32 v64, v64, v65
	v_add_f32_e32 v66, v66, v67
	v_mov_b32_e32 v73, v60
	v_mov_b32_e32 v69, v61
	v_mov_b32_e32 v65, v62
	v_mov_b32_e32 v67, v63
	v_pk_add_f32 v[60:61], v[72:73], v[68:69]
	v_pk_add_f32 v[62:63], v[64:65], v[66:67]
	s_waitcnt vmcnt(1)
	v_lshlrev_b32_e32 v70, 16, v56
	v_pk_add_f32 v[60:61], v[60:61], v[62:63]
	v_and_b32_e32 v71, 0xffff0000, v56
	v_add_f32_e32 v60, v60, v61
	v_fmamk_f32 v60, v60, 0x3a800000, v1
	v_rsq_f32_e32 v64, v60
	v_lshlrev_b32_e32 v56, 16, v57
	v_and_b32_e32 v57, 0xffff0000, v57
	v_pk_mul_f32 v[56:57], v[64:65], v[56:57] op_sel_hi:[0,1]
	v_pk_mul_f32 v[70:71], v[64:65], v[70:71] op_sel_hi:[0,1]
	s_andn2_b64 vcc, exec, s[48:49]
	s_waitcnt vmcnt(0)
	s_nop 1
	v_mov_b64_e32 v[60:61], v[124:125]
	v_mov_b64_e32 v[62:63], v[126:127]
	v_mov_b64_e32 v[66:67], v[120:121]
	v_mov_b64_e32 v[68:69], v[122:123]
	v_pk_mul_f32 v[68:69], v[56:57], v[68:69]
	v_lshlrev_b32_e32 v56, 16, v58
	v_and_b32_e32 v57, 0xffff0000, v58
	v_lshlrev_b32_e32 v58, 16, v59
	v_and_b32_e32 v59, 0xffff0000, v59
	v_pk_mul_f32 v[56:57], v[64:65], v[56:57] op_sel_hi:[0,1]
	v_pk_mul_f32 v[58:59], v[64:65], v[58:59] op_sel_hi:[0,1]
	v_pk_mul_f32 v[66:67], v[70:71], v[66:67]
	v_lshl_add_u64 v[70:71], s[24:25], 0, v[78:79]
	v_pk_mul_f32 v[56:57], v[56:57], v[60:61]
	v_pk_mul_f32 v[58:59], v[58:59], v[62:63]
	global_store_dwordx4 v[70:71], v[66:69], off
	global_store_dwordx4 v[70:71], v[56:59], off offset:16
	s_nop 0
	v_lshlrev_b32_e32 v66, 16, v52
	v_and_b32_e32 v67, 0xffff0000, v52
	v_lshlrev_b32_e32 v52, 16, v53
	v_and_b32_e32 v53, 0xffff0000, v53
	v_pk_mul_f32 v[52:53], v[64:65], v[52:53] op_sel_hi:[0,1]
	v_pk_mul_f32 v[66:67], v[64:65], v[66:67] op_sel_hi:[0,1]
	s_waitcnt vmcnt(0)
	s_nop 1
	v_mov_b64_e32 v[56:57], v[132:133]
	v_mov_b64_e32 v[58:59], v[134:135]
	v_mov_b64_e32 v[60:61], v[128:129]
	v_mov_b64_e32 v[62:63], v[130:131]
	v_pk_mul_f32 v[62:63], v[52:53], v[62:63]
	v_lshlrev_b32_e32 v52, 16, v54
	v_and_b32_e32 v53, 0xffff0000, v54
	v_lshlrev_b32_e32 v54, 16, v55
	v_and_b32_e32 v55, 0xffff0000, v55
	v_pk_mul_f32 v[52:53], v[64:65], v[52:53] op_sel_hi:[0,1]
	v_pk_mul_f32 v[54:55], v[64:65], v[54:55] op_sel_hi:[0,1]
	v_pk_mul_f32 v[60:61], v[66:67], v[60:61]
	v_pk_mul_f32 v[52:53], v[52:53], v[56:57]
	v_pk_mul_f32 v[54:55], v[54:55], v[58:59]
	global_store_dwordx4 v[70:71], v[60:63], off offset:2048
	global_store_dwordx4 v[70:71], v[52:55], off offset:2064
	s_cbranch_vccnz .LBB0_1976
	s_nop 0
	v_mov_b32_e32 v52, v29
	v_mov_b32_e32 v53, v30
	v_mov_b32_e32 v54, v28
	v_mov_b32_e32 v55, v31
	v_pk_add_f32 v[52:53], v[52:53], v[54:55]
	v_mov_b32_e32 v54, v21
	v_mov_b32_e32 v55, v22
	v_mov_b32_e32 v56, v20
	v_mov_b32_e32 v57, v23
	v_pk_add_f32 v[54:55], v[54:55], v[56:57]
	v_add_f32_e32 v52, v52, v53
	v_pk_add_f32 v[54:55], v[54:55], v[54:55] op_sel_hi:[0,1]
	v_add_f32_e32 v53, 0, v52
	v_add_f32_e32 v57, v12, v13
	v_add_f32_e32 v59, v14, v15
	v_mov_b32_e32 v56, v4
	v_mov_b32_e32 v58, v5
	v_mov_b32_e32 v54, v6
	v_mov_b32_e32 v52, v7
	v_pk_add_f32 v[56:57], v[56:57], v[58:59]
	v_pk_add_f32 v[52:53], v[54:55], v[52:53]
	v_lshlrev_b32_e32 v62, 16, v40
	v_pk_add_f32 v[52:53], v[56:57], v[52:53]
	v_and_b32_e32 v63, 0xffff0000, v40
	v_add_f32_e32 v52, v52, v53
	v_fmamk_f32 v52, v52, 0x3a800000, v1
	v_rsq_f32_e32 v56, v52
	v_lshlrev_b32_e32 v64, 16, v36
	v_and_b32_e32 v65, 0xffff0000, v36
	v_pk_mul_f32 v[62:63], v[56:57], v[62:63] op_sel_hi:[0,1]
	v_pk_mul_f32 v[64:65], v[56:57], v[64:65] op_sel_hi:[0,1]
	s_waitcnt vmcnt(0)
	s_nop 1
	v_mov_b64_e32 v[52:53], v[124:125]
	v_mov_b64_e32 v[54:55], v[126:127]
	v_mov_b64_e32 v[58:59], v[120:121]
	v_mov_b64_e32 v[60:61], v[122:123]
	v_pk_mul_f32 v[58:59], v[62:63], v[58:59]
	v_lshlrev_b32_e32 v62, 16, v41
	v_and_b32_e32 v63, 0xffff0000, v41
	v_pk_mul_f32 v[62:63], v[56:57], v[62:63] op_sel_hi:[0,1]
	v_pk_mul_f32 v[60:61], v[62:63], v[60:61]
	v_lshl_add_u64 v[62:63], s[22:23], 0, v[78:79]
	global_store_dwordx4 v[62:63], v[58:61], off
	s_nop 1
	v_lshlrev_b32_e32 v58, 16, v42
	v_and_b32_e32 v59, 0xffff0000, v42
	v_pk_mul_f32 v[58:59], v[56:57], v[58:59] op_sel_hi:[0,1]
	v_pk_mul_f32 v[52:53], v[58:59], v[52:53]
	v_lshlrev_b32_e32 v58, 16, v43
	v_and_b32_e32 v59, 0xffff0000, v43
	v_pk_mul_f32 v[58:59], v[56:57], v[58:59] op_sel_hi:[0,1]
	v_pk_mul_f32 v[54:55], v[58:59], v[54:55]
	global_store_dwordx4 v[62:63], v[52:55], off offset:16
	s_nop 0
	s_waitcnt vmcnt(0)
	s_nop 1
	v_mov_b64_e32 v[52:53], v[132:133]
	v_mov_b64_e32 v[54:55], v[134:135]
	v_mov_b64_e32 v[58:59], v[128:129]
	v_mov_b64_e32 v[60:61], v[130:131]
	v_pk_mul_f32 v[58:59], v[64:65], v[58:59]
	v_lshlrev_b32_e32 v64, 16, v37
	v_and_b32_e32 v65, 0xffff0000, v37
	v_pk_mul_f32 v[64:65], v[56:57], v[64:65] op_sel_hi:[0,1]
	v_pk_mul_f32 v[60:61], v[64:65], v[60:61]
	global_store_dwordx4 v[62:63], v[58:61], off offset:2048
	s_nop 1
	v_lshlrev_b32_e32 v58, 16, v38
	v_and_b32_e32 v59, 0xffff0000, v38
	v_pk_mul_f32 v[58:59], v[56:57], v[58:59] op_sel_hi:[0,1]
	v_pk_mul_f32 v[52:53], v[58:59], v[52:53]
	v_lshlrev_b32_e32 v58, 16, v39
	v_and_b32_e32 v59, 0xffff0000, v39
	v_pk_mul_f32 v[56:57], v[56:57], v[58:59] op_sel_hi:[0,1]
	v_pk_mul_f32 v[54:55], v[56:57], v[54:55]
	global_store_dwordx4 v[62:63], v[52:55], off offset:2064
; #define GAS __attribute__((address_space(1)))
; __device__ __forceinline__ float bflo(unsigned w) { return __uint_as_float(w << 16); }
; __device__ __forceinline__ float bfhi(unsigned w) { return __uint_as_float(w & 0xffff0000u); }
; __device__ __forceinline__ void final_norm_rows(float* y, const bf16* hz, const float* ssq, const float* gf, int m_lo, int m_hi, int widx, int nw, int lane) {
;     ...
;         for (int q = 0; q < 3; ++q) { const int m = m0 + q * nw; if (m < m_hi) { float s = 0.f;
; #pragma unroll
;             for (int j = 0; j < 4; ++j) s += (sp[q][j][0] + sp[q][j][1]) + (sp[q][j][2] + sp[q][j][3]);
;             const float r = __builtin_amdgcn_rsqf(s * (1.0f / 1024.0f) + NORM_EPS);
;             GAS f32x4* yr = (GAS f32x4*)(y + (size_t)m * DM); const GAS f32x4* gr = (const GAS f32x4*)gf;
; #pragma unroll
;             for (int j = 0; j < 2; ++j) { const v4u w = hq[q][j]; const int c = 2 * (lane + 64 * j);
;                 const f32x4 g0 = gr[c], g1 = gr[c + 1];
;                 yr[c] = (f32x4){bflo(w.x) * r * g0[0], bfhi(w.x) * r * g0[1], bflo(w.y) * r * g0[2], bfhi(w.y) * r * g0[3]};
;                 yr[c + 1] = (f32x4){bflo(w.z) * r * g1[0], bfhi(w.z) * r * g1[1], bflo(w.w) * r * g1[2], bfhi(w.w) * r * g1[3]}; } } }
.LBB0_1976:
	s_andn2_b64 vcc, exec, s[46:47]
	s_cbranch_vccnz .LBB0_1969
	v_mov_b32_e32 v52, v33
	v_mov_b32_e32 v53, v34
	v_mov_b32_e32 v54, v32
	v_mov_b32_e32 v55, v35
	v_pk_add_f32 v[52:53], v[52:53], v[54:55]
	v_mov_b32_e32 v54, v25
	v_mov_b32_e32 v55, v26
	v_mov_b32_e32 v56, v24
	v_mov_b32_e32 v57, v27
	v_pk_add_f32 v[54:55], v[54:55], v[56:57]
	v_add_f32_e32 v52, v52, v53
	v_pk_add_f32 v[54:55], v[54:55], v[54:55] op_sel_hi:[0,1]
	v_add_f32_e32 v53, 0, v52
	v_add_f32_e32 v57, v16, v17
	v_add_f32_e32 v59, v18, v19
	v_mov_b32_e32 v56, v8
	v_mov_b32_e32 v58, v9
	v_mov_b32_e32 v54, v10
	v_mov_b32_e32 v52, v11
	v_pk_add_f32 v[56:57], v[56:57], v[58:59]
	v_pk_add_f32 v[52:53], v[54:55], v[52:53]
	v_lshlrev_b32_e32 v62, 16, v48
	v_pk_add_f32 v[52:53], v[56:57], v[52:53]
	v_and_b32_e32 v63, 0xffff0000, v48
	v_add_f32_e32 v52, v52, v53
	v_fmamk_f32 v52, v52, 0x3a800000, v1
	v_rsq_f32_e32 v56, v52
	s_ashr_i32 s45, s44, 31
	s_lshl_b64 s[44:45], s[44:45], 12
	v_pk_mul_f32 v[62:63], v[56:57], v[62:63] op_sel_hi:[0,1]
	v_lshlrev_b32_e32 v64, 16, v44
	v_and_b32_e32 v65, 0xffff0000, v44
	v_pk_mul_f32 v[64:65], v[56:57], v[64:65] op_sel_hi:[0,1]
	s_waitcnt vmcnt(0)
	s_nop 1
	v_mov_b64_e32 v[52:53], v[124:125]
	v_mov_b64_e32 v[54:55], v[126:127]
	v_mov_b64_e32 v[58:59], v[120:121]
	v_mov_b64_e32 v[60:61], v[122:123]
	v_pk_mul_f32 v[58:59], v[62:63], v[58:59]
	v_lshlrev_b32_e32 v62, 16, v49
	v_and_b32_e32 v63, 0xffff0000, v49
	v_pk_mul_f32 v[62:63], v[56:57], v[62:63] op_sel_hi:[0,1]
	v_pk_mul_f32 v[60:61], v[62:63], v[60:61]
	v_lshl_add_u64 v[62:63], v[80:81], 0, s[44:45]
	global_store_dwordx4 v[62:63], v[58:61], off
	s_nop 1
	v_lshlrev_b32_e32 v58, 16, v50
	v_and_b32_e32 v59, 0xffff0000, v50
	v_pk_mul_f32 v[58:59], v[56:57], v[58:59] op_sel_hi:[0,1]
	v_pk_mul_f32 v[52:53], v[58:59], v[52:53]
	v_lshlrev_b32_e32 v58, 16, v51
	v_and_b32_e32 v59, 0xffff0000, v51
	v_pk_mul_f32 v[58:59], v[56:57], v[58:59] op_sel_hi:[0,1]
	v_pk_mul_f32 v[54:55], v[58:59], v[54:55]
	global_store_dwordx4 v[62:63], v[52:55], off offset:16
	s_nop 0
	s_waitcnt vmcnt(0)
	s_nop 1
	v_mov_b64_e32 v[52:53], v[132:133]
	v_mov_b64_e32 v[54:55], v[134:135]
	v_mov_b64_e32 v[58:59], v[128:129]
	v_mov_b64_e32 v[60:61], v[130:131]
	v_pk_mul_f32 v[58:59], v[64:65], v[58:59]
	v_lshlrev_b32_e32 v64, 16, v45
	v_and_b32_e32 v65, 0xffff0000, v45
	v_pk_mul_f32 v[64:65], v[56:57], v[64:65] op_sel_hi:[0,1]
	v_pk_mul_f32 v[60:61], v[64:65], v[60:61]
	global_store_dwordx4 v[62:63], v[58:61], off offset:2048
	s_nop 1
	v_lshlrev_b32_e32 v58, 16, v46
	v_and_b32_e32 v59, 0xffff0000, v46
	v_pk_mul_f32 v[58:59], v[56:57], v[58:59] op_sel_hi:[0,1]
	v_pk_mul_f32 v[52:53], v[58:59], v[52:53]
	v_lshlrev_b32_e32 v58, 16, v47
	v_and_b32_e32 v59, 0xffff0000, v47
	v_pk_mul_f32 v[56:57], v[56:57], v[58:59] op_sel_hi:[0,1]
	v_pk_mul_f32 v[54:55], v[56:57], v[54:55]
	global_store_dwordx4 v[62:63], v[52:55], off offset:2064
	s_branch .LBB0_1969
